# P5 K-loop: one small load per wave and iteration touching the x rows the epilogue reads (cache fill only; x is cold in HBM by then)
# baseline (speedup 1.0000x reference)
.LBB0_761:
	s_add_u32 s36, s34, 0xfff80080
	s_addc_u32 s37, s35, -1
	s_cmp_eq_u32 s58, 28
	s_cselect_b32 s43, s23, s37
	s_cselect_b32 s42, s29, s36
	s_cselect_b32 s37, s13, s57
	s_cselect_b32 s36, s31, s56
	s_and_b64 vcc, exec, s[10:11]
	s_cbranch_vccz .Lk64_trail_p5
	s_sub_u32 vcc_lo, s56, 0x80
	s_subb_u32 vcc_hi, s57, 0
	s_add_i32 m0, s44, 0x18000
	s_nop 0
	global_load_lds_dwordx4 v130, vcc
	s_add_i32 m0, s44, 0x1a000
	s_nop 0
	global_load_lds_dwordx4 v134, vcc
	s_add_u32 vcc_lo, vcc_lo, 0x20000
	s_addc_u32 vcc_hi, vcc_hi, 0
	s_add_i32 m0, s44, 0x19000
	s_nop 0
	global_load_lds_dwordx4 v130, vcc
	s_add_i32 m0, s44, 0x1b000
	s_nop 0
	global_load_lds_dwordx4 v134, vcc
	s_add_u32 vcc_lo, vcc_lo, 0x60000
	s_addc_u32 vcc_hi, vcc_hi, 0
	s_add_i32 m0, s44, 0x1c000
	s_nop 0
	global_load_lds_dwordx4 v130, vcc
	s_add_i32 m0, s44, 0x1e000
	s_nop 0
	global_load_lds_dwordx4 v134, vcc
	s_add_u32 vcc_lo, vcc_lo, 0x20000
	s_addc_u32 vcc_hi, vcc_hi, 0
	s_add_i32 m0, s44, 0x1d000
	s_nop 0
	global_load_lds_dwordx4 v130, vcc
	s_add_i32 m0, s44, 0x1f000
	s_nop 0
	global_load_lds_dwordx4 v134, vcc
	s_add_i32 vcc_lo, s58, 2
	s_and_b32 vcc_lo, vcc_lo, 30
	s_lshl_b32 vcc_lo, vcc_lo, 3
	s_lshr_b32 vcc_hi, s44, 9
	s_add_i32 vcc_lo, vcc_lo, vcc_hi
	s_lshl_b32 vcc_hi, s30, 8
	s_add_i32 vcc_lo, vcc_lo, vcc_hi
	s_lshl_b32 vcc_lo, vcc_lo, 13
	s_lshl_b32 vcc_hi, s28, 10
	s_add_i32 vcc_lo, vcc_lo, vcc_hi
	v_readlane_b32 vcc_hi, v253, 24
	s_add_u32 vcc_lo, vcc_hi, vcc_lo
	v_readlane_b32 vcc_hi, v253, 25
	s_addc_u32 vcc_hi, vcc_hi, 0
	v_and_b32_e32 v248, 15, v252
	v_lshlrev_b32_e32 v248, 6, v248
	v_bfe_u32 v249, v252, 4, 1
	v_lshl_add_u32 v248, v249, 13, v248
	s_lshr_b32 m0, s44, 2
	s_add_i32 m0, m0, 0x20000
	s_nop 0
	global_load_lds_dword v248, vcc
	ds_read_b128 v[144:147], v153 offset:0
	ds_read_b128 v[158:161], v153 offset:1024
	ds_read_b128 v[162:165], v153 offset:2048
	ds_read_b128 v[166:169], v153 offset:3072
	ds_read_b128 v[170:173], v154 offset:0
	ds_read_b128 v[174:177], v154 offset:1024
	ds_read_b128 v[178:181], v154 offset:2048
	ds_read_b128 v[182:185], v154 offset:3072
	ds_read_b128 v[186:189], v155 offset:0
	ds_read_b128 v[190:193], v155 offset:1024
	ds_read_b128 v[194:197], v155 offset:2048
	ds_read_b128 v[198:201], v155 offset:3072
	ds_read_b128 v[202:205], v155 offset:4096
	ds_read_b128 v[206:209], v155 offset:5120
	ds_read_b128 v[210:213], v155 offset:6144
	ds_read_b128 v[214:217], v155 offset:7168
	ds_read_b128 v[220:223], v155 offset:16384
	ds_read_b128 v[224:227], v155 offset:17408
	ds_read_b128 v[228:231], v155 offset:18432
	ds_read_b128 v[232:235], v155 offset:19456
	ds_read_b128 v[236:239], v155 offset:20480
	ds_read_b128 v[240:243], v155 offset:21504
	ds_read_b128 v[244:247], v155 offset:22528
	ds_read_b128 v[248:251], v155 offset:23552
	s_nop 15
	s_nop 15
	s_waitcnt lgkmcnt(0)
	s_barrier
	s_setprio 1
	v_mfma_f32_16x16x32_bf16 v[124:127], v[144:147], v[186:189], v[124:127]
	v_mfma_f32_16x16x32_bf16 v[120:123], v[162:165], v[186:189], v[120:123]
	v_mfma_f32_16x16x32_bf16 v[108:111], v[144:147], v[194:197], v[108:111]
	v_mfma_f32_16x16x32_bf16 v[104:107], v[162:165], v[194:197], v[104:107]
	v_mfma_f32_16x16x32_bf16 v[92:95], v[144:147], v[202:205], v[92:95]
	v_mfma_f32_16x16x32_bf16 v[88:91], v[162:165], v[202:205], v[88:91]
	v_mfma_f32_16x16x32_bf16 v[76:79], v[144:147], v[210:213], v[76:79]
	v_mfma_f32_16x16x32_bf16 v[72:75], v[162:165], v[210:213], v[72:75]
	v_mfma_f32_16x16x32_bf16 v[124:127], v[158:161], v[190:193], v[124:127]
	v_mfma_f32_16x16x32_bf16 v[120:123], v[166:169], v[190:193], v[120:123]
	v_mfma_f32_16x16x32_bf16 v[108:111], v[158:161], v[198:201], v[108:111]
	v_mfma_f32_16x16x32_bf16 v[104:107], v[166:169], v[198:201], v[104:107]
	v_mfma_f32_16x16x32_bf16 v[92:95], v[158:161], v[206:209], v[92:95]
	v_mfma_f32_16x16x32_bf16 v[88:91], v[166:169], v[206:209], v[88:91]
	v_mfma_f32_16x16x32_bf16 v[76:79], v[158:161], v[214:217], v[76:79]
	v_mfma_f32_16x16x32_bf16 v[72:75], v[166:169], v[214:217], v[72:75]
	s_setprio 0
	s_setprio 1
	v_mfma_f32_16x16x32_bf16 v[116:119], v[170:173], v[186:189], v[116:119]
	v_mfma_f32_16x16x32_bf16 v[112:115], v[178:181], v[186:189], v[112:115]
	v_mfma_f32_16x16x32_bf16 v[100:103], v[170:173], v[194:197], v[100:103]
	v_mfma_f32_16x16x32_bf16 v[96:99], v[178:181], v[194:197], v[96:99]
	v_mfma_f32_16x16x32_bf16 v[84:87], v[170:173], v[202:205], v[84:87]
	v_mfma_f32_16x16x32_bf16 v[80:83], v[178:181], v[202:205], v[80:83]
	v_mfma_f32_16x16x32_bf16 v[68:71], v[170:173], v[210:213], v[68:71]
	v_mfma_f32_16x16x32_bf16 v[64:67], v[178:181], v[210:213], v[64:67]
	v_mfma_f32_16x16x32_bf16 v[116:119], v[174:177], v[190:193], v[116:119]
	v_mfma_f32_16x16x32_bf16 v[112:115], v[182:185], v[190:193], v[112:115]
	v_mfma_f32_16x16x32_bf16 v[100:103], v[174:177], v[198:201], v[100:103]
	v_mfma_f32_16x16x32_bf16 v[96:99], v[182:185], v[198:201], v[96:99]
	v_mfma_f32_16x16x32_bf16 v[84:87], v[174:177], v[206:209], v[84:87]
	v_mfma_f32_16x16x32_bf16 v[80:83], v[182:185], v[206:209], v[80:83]
	v_mfma_f32_16x16x32_bf16 v[68:71], v[174:177], v[214:217], v[68:71]
	v_mfma_f32_16x16x32_bf16 v[64:67], v[182:185], v[214:217], v[64:67]
	s_setprio 0
	s_setprio 1
	v_mfma_f32_16x16x32_bf16 v[60:63], v[144:147], v[220:223], v[60:63]
	v_mfma_f32_16x16x32_bf16 v[56:59], v[162:165], v[220:223], v[56:59]
	v_mfma_f32_16x16x32_bf16 v[44:47], v[144:147], v[228:231], v[44:47]
	v_mfma_f32_16x16x32_bf16 v[40:43], v[162:165], v[228:231], v[40:43]
	v_mfma_f32_16x16x32_bf16 v[28:31], v[144:147], v[236:239], v[28:31]
	v_mfma_f32_16x16x32_bf16 v[24:27], v[162:165], v[236:239], v[24:27]
	v_mfma_f32_16x16x32_bf16 v[12:15], v[144:147], v[244:247], v[12:15]
	v_mfma_f32_16x16x32_bf16 v[8:11], v[162:165], v[244:247], v[8:11]
	v_mfma_f32_16x16x32_bf16 v[60:63], v[158:161], v[224:227], v[60:63]
	v_mfma_f32_16x16x32_bf16 v[56:59], v[166:169], v[224:227], v[56:59]
	v_mfma_f32_16x16x32_bf16 v[44:47], v[158:161], v[232:235], v[44:47]
	v_mfma_f32_16x16x32_bf16 v[40:43], v[166:169], v[232:235], v[40:43]
	v_mfma_f32_16x16x32_bf16 v[28:31], v[158:161], v[240:243], v[28:31]
	v_mfma_f32_16x16x32_bf16 v[24:27], v[166:169], v[240:243], v[24:27]
	v_mfma_f32_16x16x32_bf16 v[12:15], v[158:161], v[248:251], v[12:15]
	v_mfma_f32_16x16x32_bf16 v[8:11], v[166:169], v[248:251], v[8:11]
	s_setprio 0
	s_setprio 1
	v_mfma_f32_16x16x32_bf16 v[52:55], v[170:173], v[220:223], v[52:55]
	v_mfma_f32_16x16x32_bf16 v[48:51], v[178:181], v[220:223], v[48:51]
	v_mfma_f32_16x16x32_bf16 v[36:39], v[170:173], v[228:231], v[36:39]
	v_mfma_f32_16x16x32_bf16 v[32:35], v[178:181], v[228:231], v[32:35]
	v_mfma_f32_16x16x32_bf16 v[20:23], v[170:173], v[236:239], v[20:23]
	v_mfma_f32_16x16x32_bf16 v[16:19], v[178:181], v[236:239], v[16:19]
	v_mfma_f32_16x16x32_bf16 v[4:7], v[170:173], v[244:247], v[4:7]
	v_mfma_f32_16x16x32_bf16 v[0:3], v[178:181], v[244:247], v[0:3]
	v_mfma_f32_16x16x32_bf16 v[52:55], v[174:177], v[224:227], v[52:55]
	v_mfma_f32_16x16x32_bf16 v[48:51], v[182:185], v[224:227], v[48:51]
	v_mfma_f32_16x16x32_bf16 v[36:39], v[174:177], v[232:235], v[36:39]
	v_mfma_f32_16x16x32_bf16 v[32:35], v[182:185], v[232:235], v[32:35]
	v_mfma_f32_16x16x32_bf16 v[20:23], v[174:177], v[240:243], v[20:23]
	v_mfma_f32_16x16x32_bf16 v[16:19], v[182:185], v[240:243], v[16:19]
	v_mfma_f32_16x16x32_bf16 v[4:7], v[174:177], v[248:251], v[4:7]
	v_mfma_f32_16x16x32_bf16 v[0:3], v[182:185], v[248:251], v[0:3]
	s_setprio 0
	s_waitcnt vmcnt(1)
	s_barrier
	s_add_u32 vcc_lo, s36, 0x0
	s_addc_u32 vcc_hi, s37, 0
	s_add_i32 m0, s44, 0x10000
	s_nop 0
	global_load_lds_dwordx4 v130, vcc
	s_add_i32 m0, s44, 0x12000
	s_nop 0
	global_load_lds_dwordx4 v134, vcc
	s_add_u32 vcc_lo, vcc_lo, 0x20000
	s_addc_u32 vcc_hi, vcc_hi, 0
	s_add_i32 m0, s44, 0x11000
	s_nop 0
	global_load_lds_dwordx4 v130, vcc
	s_add_i32 m0, s44, 0x13000
	s_nop 0
	global_load_lds_dwordx4 v134, vcc
	s_add_u32 vcc_lo, vcc_lo, 0x60000
	s_addc_u32 vcc_hi, vcc_hi, 0
	s_add_i32 m0, s44, 0x14000
	s_nop 0
	global_load_lds_dwordx4 v130, vcc
	s_add_i32 m0, s44, 0x16000
	s_nop 0
	global_load_lds_dwordx4 v134, vcc
	s_add_u32 vcc_lo, vcc_lo, 0x20000
	s_addc_u32 vcc_hi, vcc_hi, 0
	s_add_i32 m0, s44, 0x15000
	s_nop 0
	global_load_lds_dwordx4 v130, vcc
	s_add_i32 m0, s44, 0x17000
	s_nop 0
	global_load_lds_dwordx4 v134, vcc
	ds_read_b128 v[144:147], v153 offset:32768
	ds_read_b128 v[158:161], v153 offset:33792
	ds_read_b128 v[162:165], v153 offset:34816
	ds_read_b128 v[166:169], v153 offset:35840
	ds_read_b128 v[170:173], v154 offset:32768
	ds_read_b128 v[174:177], v154 offset:33792
	ds_read_b128 v[178:181], v154 offset:34816
	ds_read_b128 v[182:185], v154 offset:35840
	ds_read_b128 v[186:189], v155 offset:32768
	ds_read_b128 v[190:193], v155 offset:33792
	ds_read_b128 v[194:197], v155 offset:34816
	ds_read_b128 v[198:201], v155 offset:35840
	ds_read_b128 v[202:205], v155 offset:36864
	ds_read_b128 v[206:209], v155 offset:37888
	ds_read_b128 v[210:213], v155 offset:38912
	ds_read_b128 v[214:217], v155 offset:39936
	ds_read_b128 v[220:223], v155 offset:49152
	ds_read_b128 v[224:227], v155 offset:50176
	ds_read_b128 v[228:231], v155 offset:51200
	ds_read_b128 v[232:235], v155 offset:52224
	ds_read_b128 v[236:239], v155 offset:53248
	ds_read_b128 v[240:243], v155 offset:54272
	ds_read_b128 v[244:247], v155 offset:55296
	ds_read_b128 v[248:251], v155 offset:56320
	s_nop 15
	s_nop 15
	s_waitcnt lgkmcnt(0)
	s_barrier
	s_setprio 1
	v_mfma_f32_16x16x32_bf16 v[124:127], v[144:147], v[186:189], v[124:127]
	v_mfma_f32_16x16x32_bf16 v[120:123], v[162:165], v[186:189], v[120:123]
	v_mfma_f32_16x16x32_bf16 v[108:111], v[144:147], v[194:197], v[108:111]
	v_mfma_f32_16x16x32_bf16 v[104:107], v[162:165], v[194:197], v[104:107]
	v_mfma_f32_16x16x32_bf16 v[92:95], v[144:147], v[202:205], v[92:95]
	v_mfma_f32_16x16x32_bf16 v[88:91], v[162:165], v[202:205], v[88:91]
	v_mfma_f32_16x16x32_bf16 v[76:79], v[144:147], v[210:213], v[76:79]
	v_mfma_f32_16x16x32_bf16 v[72:75], v[162:165], v[210:213], v[72:75]
	v_mfma_f32_16x16x32_bf16 v[124:127], v[158:161], v[190:193], v[124:127]
	v_mfma_f32_16x16x32_bf16 v[120:123], v[166:169], v[190:193], v[120:123]
	v_mfma_f32_16x16x32_bf16 v[108:111], v[158:161], v[198:201], v[108:111]
	v_mfma_f32_16x16x32_bf16 v[104:107], v[166:169], v[198:201], v[104:107]
	v_mfma_f32_16x16x32_bf16 v[92:95], v[158:161], v[206:209], v[92:95]
	v_mfma_f32_16x16x32_bf16 v[88:91], v[166:169], v[206:209], v[88:91]
	v_mfma_f32_16x16x32_bf16 v[76:79], v[158:161], v[214:217], v[76:79]
	v_mfma_f32_16x16x32_bf16 v[72:75], v[166:169], v[214:217], v[72:75]
	s_setprio 0
	s_setprio 1
	v_mfma_f32_16x16x32_bf16 v[116:119], v[170:173], v[186:189], v[116:119]
	v_mfma_f32_16x16x32_bf16 v[112:115], v[178:181], v[186:189], v[112:115]
	v_mfma_f32_16x16x32_bf16 v[100:103], v[170:173], v[194:197], v[100:103]
	v_mfma_f32_16x16x32_bf16 v[96:99], v[178:181], v[194:197], v[96:99]
	v_mfma_f32_16x16x32_bf16 v[84:87], v[170:173], v[202:205], v[84:87]
	v_mfma_f32_16x16x32_bf16 v[80:83], v[178:181], v[202:205], v[80:83]
	v_mfma_f32_16x16x32_bf16 v[68:71], v[170:173], v[210:213], v[68:71]
	v_mfma_f32_16x16x32_bf16 v[64:67], v[178:181], v[210:213], v[64:67]
	v_mfma_f32_16x16x32_bf16 v[116:119], v[174:177], v[190:193], v[116:119]
	v_mfma_f32_16x16x32_bf16 v[112:115], v[182:185], v[190:193], v[112:115]
	v_mfma_f32_16x16x32_bf16 v[100:103], v[174:177], v[198:201], v[100:103]
	v_mfma_f32_16x16x32_bf16 v[96:99], v[182:185], v[198:201], v[96:99]
	v_mfma_f32_16x16x32_bf16 v[84:87], v[174:177], v[206:209], v[84:87]
	v_mfma_f32_16x16x32_bf16 v[80:83], v[182:185], v[206:209], v[80:83]
	v_mfma_f32_16x16x32_bf16 v[68:71], v[174:177], v[214:217], v[68:71]
	v_mfma_f32_16x16x32_bf16 v[64:67], v[182:185], v[214:217], v[64:67]
	s_setprio 0
	s_setprio 1
	v_mfma_f32_16x16x32_bf16 v[60:63], v[144:147], v[220:223], v[60:63]
	v_mfma_f32_16x16x32_bf16 v[56:59], v[162:165], v[220:223], v[56:59]
	v_mfma_f32_16x16x32_bf16 v[44:47], v[144:147], v[228:231], v[44:47]
	v_mfma_f32_16x16x32_bf16 v[40:43], v[162:165], v[228:231], v[40:43]
	v_mfma_f32_16x16x32_bf16 v[28:31], v[144:147], v[236:239], v[28:31]
	v_mfma_f32_16x16x32_bf16 v[24:27], v[162:165], v[236:239], v[24:27]
	v_mfma_f32_16x16x32_bf16 v[12:15], v[144:147], v[244:247], v[12:15]
	v_mfma_f32_16x16x32_bf16 v[8:11], v[162:165], v[244:247], v[8:11]
	v_mfma_f32_16x16x32_bf16 v[60:63], v[158:161], v[224:227], v[60:63]
	v_mfma_f32_16x16x32_bf16 v[56:59], v[166:169], v[224:227], v[56:59]
	v_mfma_f32_16x16x32_bf16 v[44:47], v[158:161], v[232:235], v[44:47]
	v_mfma_f32_16x16x32_bf16 v[40:43], v[166:169], v[232:235], v[40:43]
	v_mfma_f32_16x16x32_bf16 v[28:31], v[158:161], v[240:243], v[28:31]
	v_mfma_f32_16x16x32_bf16 v[24:27], v[166:169], v[240:243], v[24:27]
	v_mfma_f32_16x16x32_bf16 v[12:15], v[158:161], v[248:251], v[12:15]
	v_mfma_f32_16x16x32_bf16 v[8:11], v[166:169], v[248:251], v[8:11]
	s_setprio 0
	s_setprio 1
	v_mfma_f32_16x16x32_bf16 v[52:55], v[170:173], v[220:223], v[52:55]
	v_mfma_f32_16x16x32_bf16 v[48:51], v[178:181], v[220:223], v[48:51]
	v_mfma_f32_16x16x32_bf16 v[36:39], v[170:173], v[228:231], v[36:39]
	v_mfma_f32_16x16x32_bf16 v[32:35], v[178:181], v[228:231], v[32:35]
	v_mfma_f32_16x16x32_bf16 v[20:23], v[170:173], v[236:239], v[20:23]
	v_mfma_f32_16x16x32_bf16 v[16:19], v[178:181], v[236:239], v[16:19]
	v_mfma_f32_16x16x32_bf16 v[4:7], v[170:173], v[244:247], v[4:7]
	v_mfma_f32_16x16x32_bf16 v[0:3], v[178:181], v[244:247], v[0:3]
	v_mfma_f32_16x16x32_bf16 v[52:55], v[174:177], v[224:227], v[52:55]
	v_mfma_f32_16x16x32_bf16 v[48:51], v[182:185], v[224:227], v[48:51]
	v_mfma_f32_16x16x32_bf16 v[36:39], v[174:177], v[232:235], v[36:39]
	v_mfma_f32_16x16x32_bf16 v[32:35], v[182:185], v[232:235], v[32:35]
	v_mfma_f32_16x16x32_bf16 v[20:23], v[174:177], v[240:243], v[20:23]
	v_mfma_f32_16x16x32_bf16 v[16:19], v[182:185], v[240:243], v[16:19]
	v_mfma_f32_16x16x32_bf16 v[4:7], v[174:177], v[248:251], v[4:7]
	v_mfma_f32_16x16x32_bf16 v[0:3], v[182:185], v[248:251], v[0:3]
	s_setprio 0
	s_waitcnt vmcnt(0)
	s_barrier
	s_add_i32 s58, s58, 2
	s_add_u32 s34, s34, 0x100
	s_addc_u32 s35, s35, 0
	s_add_u32 s56, s56, 0x100
	s_addc_u32 s57, s57, 0
	s_cmp_gt_u32 s58, 29
	s_cbranch_scc0 .LBB0_761
	s_branch .Lk64_done_p5
.Lk64_trail_p5:
	s_sub_u32 vcc_lo, s34, 0x80000
	s_subb_u32 vcc_hi, s35, 0
	s_add_i32 m0, s44, 0xa000
	s_nop 0
	global_load_lds_dwordx4 v132, vcc
	s_add_u32 vcc_lo, vcc_lo, 0x20000
	s_addc_u32 vcc_hi, vcc_hi, 0
	s_add_i32 m0, s44, 0x9000
	s_nop 0
	global_load_lds_dwordx4 v128, vcc
	s_add_u32 vcc_lo, vcc_lo, 0x60000
	s_addc_u32 vcc_hi, vcc_hi, 0
	s_add_i32 m0, s44, 0xe000
	s_nop 0
	global_load_lds_dwordx4 v132, vcc
	s_add_u32 vcc_lo, vcc_lo, 0x20000
	s_addc_u32 vcc_hi, vcc_hi, 0
	s_add_i32 m0, s44, 0xd000
	s_nop 0
	global_load_lds_dwordx4 v128, vcc
	s_add_u32 vcc_lo, s42, 0x0
	s_addc_u32 vcc_hi, s43, 0
	s_mov_b32 m0, s44
	s_nop 0
	global_load_lds_dwordx4 v128, vcc
	s_sub_u32 vcc_lo, vcc_lo, 0x20000
	s_subb_u32 vcc_hi, vcc_hi, 0
	s_sub_i32 m0, s44, 0x1000
	s_nop 0
	global_load_lds_dwordx4 v128, vcc
	s_add_u32 vcc_lo, vcc_lo, 0xa0000
	s_addc_u32 vcc_hi, vcc_hi, 0
	s_add_i32 m0, s44, 0x4000
	s_nop 0
	global_load_lds_dwordx4 v128, vcc
	s_sub_u32 vcc_lo, vcc_lo, 0x20000
	s_subb_u32 vcc_hi, vcc_hi, 0
	s_add_i32 m0, s44, 0x3000
	s_nop 0
	global_load_lds_dwordx4 v128, vcc
	s_add_i32 vcc_lo, s58, 2
	s_and_b32 vcc_lo, vcc_lo, 30
	s_lshl_b32 vcc_lo, vcc_lo, 3
	s_lshr_b32 vcc_hi, s44, 9
	s_add_i32 vcc_lo, vcc_lo, vcc_hi
	s_lshl_b32 vcc_hi, s30, 8
	s_add_i32 vcc_lo, vcc_lo, vcc_hi
	s_lshl_b32 vcc_lo, vcc_lo, 13
	s_lshl_b32 vcc_hi, s28, 10
	s_add_i32 vcc_lo, vcc_lo, vcc_hi
	v_readlane_b32 vcc_hi, v253, 24
	s_add_u32 vcc_lo, vcc_hi, vcc_lo
	v_readlane_b32 vcc_hi, v253, 25
	s_addc_u32 vcc_hi, vcc_hi, 0
	v_and_b32_e32 v248, 15, v252
	v_lshlrev_b32_e32 v248, 6, v248
	v_bfe_u32 v249, v252, 4, 1
	v_lshl_add_u32 v248, v249, 13, v248
	s_lshr_b32 m0, s44, 2
	s_add_i32 m0, m0, 0x20000
	s_nop 0
	global_load_lds_dword v248, vcc
	ds_read_b128 v[144:147], v153 offset:0
	ds_read_b128 v[158:161], v153 offset:1024
	ds_read_b128 v[162:165], v153 offset:2048
	ds_read_b128 v[166:169], v153 offset:3072
	ds_read_b128 v[170:173], v154 offset:0
	ds_read_b128 v[174:177], v154 offset:1024
	ds_read_b128 v[178:181], v154 offset:2048
	ds_read_b128 v[182:185], v154 offset:3072
	ds_read_b128 v[186:189], v155 offset:0
	ds_read_b128 v[190:193], v155 offset:1024
	ds_read_b128 v[194:197], v155 offset:2048
	ds_read_b128 v[198:201], v155 offset:3072
	ds_read_b128 v[202:205], v155 offset:4096
	ds_read_b128 v[206:209], v155 offset:5120
	ds_read_b128 v[210:213], v155 offset:6144
	ds_read_b128 v[214:217], v155 offset:7168
	ds_read_b128 v[220:223], v155 offset:16384
	ds_read_b128 v[224:227], v155 offset:17408
	ds_read_b128 v[228:231], v155 offset:18432
	ds_read_b128 v[232:235], v155 offset:19456
	ds_read_b128 v[236:239], v155 offset:20480
	ds_read_b128 v[240:243], v155 offset:21504
	ds_read_b128 v[244:247], v155 offset:22528
	ds_read_b128 v[248:251], v155 offset:23552
	s_nop 15
	s_nop 15
	s_waitcnt lgkmcnt(0)
	s_barrier
	s_setprio 1
	v_mfma_f32_16x16x32_bf16 v[124:127], v[144:147], v[186:189], v[124:127]
	v_mfma_f32_16x16x32_bf16 v[120:123], v[162:165], v[186:189], v[120:123]
	v_mfma_f32_16x16x32_bf16 v[108:111], v[144:147], v[194:197], v[108:111]
	v_mfma_f32_16x16x32_bf16 v[104:107], v[162:165], v[194:197], v[104:107]
	v_mfma_f32_16x16x32_bf16 v[92:95], v[144:147], v[202:205], v[92:95]
	v_mfma_f32_16x16x32_bf16 v[88:91], v[162:165], v[202:205], v[88:91]
	v_mfma_f32_16x16x32_bf16 v[76:79], v[144:147], v[210:213], v[76:79]
	v_mfma_f32_16x16x32_bf16 v[72:75], v[162:165], v[210:213], v[72:75]
	v_mfma_f32_16x16x32_bf16 v[124:127], v[158:161], v[190:193], v[124:127]
	v_mfma_f32_16x16x32_bf16 v[120:123], v[166:169], v[190:193], v[120:123]
	v_mfma_f32_16x16x32_bf16 v[108:111], v[158:161], v[198:201], v[108:111]
	v_mfma_f32_16x16x32_bf16 v[104:107], v[166:169], v[198:201], v[104:107]
	v_mfma_f32_16x16x32_bf16 v[92:95], v[158:161], v[206:209], v[92:95]
	v_mfma_f32_16x16x32_bf16 v[88:91], v[166:169], v[206:209], v[88:91]
	v_mfma_f32_16x16x32_bf16 v[76:79], v[158:161], v[214:217], v[76:79]
	v_mfma_f32_16x16x32_bf16 v[72:75], v[166:169], v[214:217], v[72:75]
	s_setprio 0
	s_setprio 1
	v_mfma_f32_16x16x32_bf16 v[116:119], v[170:173], v[186:189], v[116:119]
	v_mfma_f32_16x16x32_bf16 v[112:115], v[178:181], v[186:189], v[112:115]
	v_mfma_f32_16x16x32_bf16 v[100:103], v[170:173], v[194:197], v[100:103]
	v_mfma_f32_16x16x32_bf16 v[96:99], v[178:181], v[194:197], v[96:99]
	v_mfma_f32_16x16x32_bf16 v[84:87], v[170:173], v[202:205], v[84:87]
	v_mfma_f32_16x16x32_bf16 v[80:83], v[178:181], v[202:205], v[80:83]
	v_mfma_f32_16x16x32_bf16 v[68:71], v[170:173], v[210:213], v[68:71]
	v_mfma_f32_16x16x32_bf16 v[64:67], v[178:181], v[210:213], v[64:67]
	v_mfma_f32_16x16x32_bf16 v[116:119], v[174:177], v[190:193], v[116:119]
	v_mfma_f32_16x16x32_bf16 v[112:115], v[182:185], v[190:193], v[112:115]
	v_mfma_f32_16x16x32_bf16 v[100:103], v[174:177], v[198:201], v[100:103]
	v_mfma_f32_16x16x32_bf16 v[96:99], v[182:185], v[198:201], v[96:99]
	v_mfma_f32_16x16x32_bf16 v[84:87], v[174:177], v[206:209], v[84:87]
	v_mfma_f32_16x16x32_bf16 v[80:83], v[182:185], v[206:209], v[80:83]
	v_mfma_f32_16x16x32_bf16 v[68:71], v[174:177], v[214:217], v[68:71]
	v_mfma_f32_16x16x32_bf16 v[64:67], v[182:185], v[214:217], v[64:67]
	s_setprio 0
	s_setprio 1
	v_mfma_f32_16x16x32_bf16 v[60:63], v[144:147], v[220:223], v[60:63]
	v_mfma_f32_16x16x32_bf16 v[56:59], v[162:165], v[220:223], v[56:59]
	v_mfma_f32_16x16x32_bf16 v[44:47], v[144:147], v[228:231], v[44:47]
	v_mfma_f32_16x16x32_bf16 v[40:43], v[162:165], v[228:231], v[40:43]
	v_mfma_f32_16x16x32_bf16 v[28:31], v[144:147], v[236:239], v[28:31]
	v_mfma_f32_16x16x32_bf16 v[24:27], v[162:165], v[236:239], v[24:27]
	v_mfma_f32_16x16x32_bf16 v[12:15], v[144:147], v[244:247], v[12:15]
	v_mfma_f32_16x16x32_bf16 v[8:11], v[162:165], v[244:247], v[8:11]
	v_mfma_f32_16x16x32_bf16 v[60:63], v[158:161], v[224:227], v[60:63]
	v_mfma_f32_16x16x32_bf16 v[56:59], v[166:169], v[224:227], v[56:59]
	v_mfma_f32_16x16x32_bf16 v[44:47], v[158:161], v[232:235], v[44:47]
	v_mfma_f32_16x16x32_bf16 v[40:43], v[166:169], v[232:235], v[40:43]
	v_mfma_f32_16x16x32_bf16 v[28:31], v[158:161], v[240:243], v[28:31]
	v_mfma_f32_16x16x32_bf16 v[24:27], v[166:169], v[240:243], v[24:27]
	v_mfma_f32_16x16x32_bf16 v[12:15], v[158:161], v[248:251], v[12:15]
	v_mfma_f32_16x16x32_bf16 v[8:11], v[166:169], v[248:251], v[8:11]
	s_setprio 0
	s_setprio 1
	v_mfma_f32_16x16x32_bf16 v[52:55], v[170:173], v[220:223], v[52:55]
	v_mfma_f32_16x16x32_bf16 v[48:51], v[178:181], v[220:223], v[48:51]
	v_mfma_f32_16x16x32_bf16 v[36:39], v[170:173], v[228:231], v[36:39]
	v_mfma_f32_16x16x32_bf16 v[32:35], v[178:181], v[228:231], v[32:35]
	v_mfma_f32_16x16x32_bf16 v[20:23], v[170:173], v[236:239], v[20:23]
	v_mfma_f32_16x16x32_bf16 v[16:19], v[178:181], v[236:239], v[16:19]
	v_mfma_f32_16x16x32_bf16 v[4:7], v[170:173], v[244:247], v[4:7]
	v_mfma_f32_16x16x32_bf16 v[0:3], v[178:181], v[244:247], v[0:3]
	v_mfma_f32_16x16x32_bf16 v[52:55], v[174:177], v[224:227], v[52:55]
	v_mfma_f32_16x16x32_bf16 v[48:51], v[182:185], v[224:227], v[48:51]
	v_mfma_f32_16x16x32_bf16 v[36:39], v[174:177], v[232:235], v[36:39]
	v_mfma_f32_16x16x32_bf16 v[32:35], v[182:185], v[232:235], v[32:35]
	v_mfma_f32_16x16x32_bf16 v[20:23], v[174:177], v[240:243], v[20:23]
	v_mfma_f32_16x16x32_bf16 v[16:19], v[182:185], v[240:243], v[16:19]
	v_mfma_f32_16x16x32_bf16 v[4:7], v[174:177], v[248:251], v[4:7]
	v_mfma_f32_16x16x32_bf16 v[0:3], v[182:185], v[248:251], v[0:3]
	s_setprio 0
	s_waitcnt vmcnt(1)
	s_barrier
	s_add_u32 vcc_lo, s42, 0x0
	s_addc_u32 vcc_hi, s43, 0
	s_add_i32 m0, s44, 0x2000
	s_nop 0
	global_load_lds_dwordx4 v132, vcc
	s_add_u32 vcc_lo, vcc_lo, 0x20000
	s_addc_u32 vcc_hi, vcc_hi, 0
	s_add_i32 m0, s44, 0x1000
	s_nop 0
	global_load_lds_dwordx4 v128, vcc
	s_add_u32 vcc_lo, vcc_lo, 0x60000
	s_addc_u32 vcc_hi, vcc_hi, 0
	s_add_i32 m0, s44, 0x6000
	s_nop 0
	global_load_lds_dwordx4 v132, vcc
	s_add_u32 vcc_lo, vcc_lo, 0x20000
	s_addc_u32 vcc_hi, vcc_hi, 0
	s_add_i32 m0, s44, 0x5000
	s_nop 0
	global_load_lds_dwordx4 v128, vcc
	s_add_u32 vcc_lo, s42, 0x80
	s_addc_u32 vcc_hi, s43, 0
	s_add_i32 m0, s44, 0x8000
	s_nop 0
	global_load_lds_dwordx4 v128, vcc
	s_sub_u32 vcc_lo, vcc_lo, 0x20000
	s_subb_u32 vcc_hi, vcc_hi, 0
	s_add_i32 m0, s44, 0x7000
	s_nop 0
	global_load_lds_dwordx4 v128, vcc
	s_add_u32 vcc_lo, vcc_lo, 0xa0000
	s_addc_u32 vcc_hi, vcc_hi, 0
	s_add_i32 m0, s44, 0xc000
	s_nop 0
	global_load_lds_dwordx4 v128, vcc
	s_sub_u32 vcc_lo, vcc_lo, 0x20000
	s_subb_u32 vcc_hi, vcc_hi, 0
	s_add_i32 m0, s44, 0xb000
	s_nop 0
	global_load_lds_dwordx4 v128, vcc
	ds_read_b128 v[144:147], v153 offset:32768
	ds_read_b128 v[158:161], v153 offset:33792
	ds_read_b128 v[162:165], v153 offset:34816
	ds_read_b128 v[166:169], v153 offset:35840
	ds_read_b128 v[170:173], v154 offset:32768
	ds_read_b128 v[174:177], v154 offset:33792
	ds_read_b128 v[178:181], v154 offset:34816
	ds_read_b128 v[182:185], v154 offset:35840
	ds_read_b128 v[186:189], v155 offset:32768
	ds_read_b128 v[190:193], v155 offset:33792
	ds_read_b128 v[194:197], v155 offset:34816
	ds_read_b128 v[198:201], v155 offset:35840
	ds_read_b128 v[202:205], v155 offset:36864
	ds_read_b128 v[206:209], v155 offset:37888
	ds_read_b128 v[210:213], v155 offset:38912
	ds_read_b128 v[214:217], v155 offset:39936
	ds_read_b128 v[220:223], v155 offset:49152
	ds_read_b128 v[224:227], v155 offset:50176
	ds_read_b128 v[228:231], v155 offset:51200
	ds_read_b128 v[232:235], v155 offset:52224
	ds_read_b128 v[236:239], v155 offset:53248
	ds_read_b128 v[240:243], v155 offset:54272
	ds_read_b128 v[244:247], v155 offset:55296
	ds_read_b128 v[248:251], v155 offset:56320
	s_nop 15
	s_nop 15
	s_waitcnt lgkmcnt(0)
	s_barrier
	s_setprio 1
	v_mfma_f32_16x16x32_bf16 v[124:127], v[144:147], v[186:189], v[124:127]
	v_mfma_f32_16x16x32_bf16 v[120:123], v[162:165], v[186:189], v[120:123]
	v_mfma_f32_16x16x32_bf16 v[108:111], v[144:147], v[194:197], v[108:111]
	v_mfma_f32_16x16x32_bf16 v[104:107], v[162:165], v[194:197], v[104:107]
	v_mfma_f32_16x16x32_bf16 v[92:95], v[144:147], v[202:205], v[92:95]
	v_mfma_f32_16x16x32_bf16 v[88:91], v[162:165], v[202:205], v[88:91]
	v_mfma_f32_16x16x32_bf16 v[76:79], v[144:147], v[210:213], v[76:79]
	v_mfma_f32_16x16x32_bf16 v[72:75], v[162:165], v[210:213], v[72:75]
	v_mfma_f32_16x16x32_bf16 v[124:127], v[158:161], v[190:193], v[124:127]
	v_mfma_f32_16x16x32_bf16 v[120:123], v[166:169], v[190:193], v[120:123]
	v_mfma_f32_16x16x32_bf16 v[108:111], v[158:161], v[198:201], v[108:111]
	v_mfma_f32_16x16x32_bf16 v[104:107], v[166:169], v[198:201], v[104:107]
	v_mfma_f32_16x16x32_bf16 v[92:95], v[158:161], v[206:209], v[92:95]
	v_mfma_f32_16x16x32_bf16 v[88:91], v[166:169], v[206:209], v[88:91]
	v_mfma_f32_16x16x32_bf16 v[76:79], v[158:161], v[214:217], v[76:79]
	v_mfma_f32_16x16x32_bf16 v[72:75], v[166:169], v[214:217], v[72:75]
	s_setprio 0
	s_setprio 1
	v_mfma_f32_16x16x32_bf16 v[116:119], v[170:173], v[186:189], v[116:119]
	v_mfma_f32_16x16x32_bf16 v[112:115], v[178:181], v[186:189], v[112:115]
	v_mfma_f32_16x16x32_bf16 v[100:103], v[170:173], v[194:197], v[100:103]
	v_mfma_f32_16x16x32_bf16 v[96:99], v[178:181], v[194:197], v[96:99]
	v_mfma_f32_16x16x32_bf16 v[84:87], v[170:173], v[202:205], v[84:87]
	v_mfma_f32_16x16x32_bf16 v[80:83], v[178:181], v[202:205], v[80:83]
	v_mfma_f32_16x16x32_bf16 v[68:71], v[170:173], v[210:213], v[68:71]
	v_mfma_f32_16x16x32_bf16 v[64:67], v[178:181], v[210:213], v[64:67]
	v_mfma_f32_16x16x32_bf16 v[116:119], v[174:177], v[190:193], v[116:119]
	v_mfma_f32_16x16x32_bf16 v[112:115], v[182:185], v[190:193], v[112:115]
	v_mfma_f32_16x16x32_bf16 v[100:103], v[174:177], v[198:201], v[100:103]
	v_mfma_f32_16x16x32_bf16 v[96:99], v[182:185], v[198:201], v[96:99]
	v_mfma_f32_16x16x32_bf16 v[84:87], v[174:177], v[206:209], v[84:87]
	v_mfma_f32_16x16x32_bf16 v[80:83], v[182:185], v[206:209], v[80:83]
	v_mfma_f32_16x16x32_bf16 v[68:71], v[174:177], v[214:217], v[68:71]
	v_mfma_f32_16x16x32_bf16 v[64:67], v[182:185], v[214:217], v[64:67]
	s_setprio 0
	s_setprio 1
	v_mfma_f32_16x16x32_bf16 v[60:63], v[144:147], v[220:223], v[60:63]
	v_mfma_f32_16x16x32_bf16 v[56:59], v[162:165], v[220:223], v[56:59]
	v_mfma_f32_16x16x32_bf16 v[44:47], v[144:147], v[228:231], v[44:47]
	v_mfma_f32_16x16x32_bf16 v[40:43], v[162:165], v[228:231], v[40:43]
	v_mfma_f32_16x16x32_bf16 v[28:31], v[144:147], v[236:239], v[28:31]
	v_mfma_f32_16x16x32_bf16 v[24:27], v[162:165], v[236:239], v[24:27]
	v_mfma_f32_16x16x32_bf16 v[12:15], v[144:147], v[244:247], v[12:15]
	v_mfma_f32_16x16x32_bf16 v[8:11], v[162:165], v[244:247], v[8:11]
	v_mfma_f32_16x16x32_bf16 v[60:63], v[158:161], v[224:227], v[60:63]
	v_mfma_f32_16x16x32_bf16 v[56:59], v[166:169], v[224:227], v[56:59]
	v_mfma_f32_16x16x32_bf16 v[44:47], v[158:161], v[232:235], v[44:47]
	v_mfma_f32_16x16x32_bf16 v[40:43], v[166:169], v[232:235], v[40:43]
	v_mfma_f32_16x16x32_bf16 v[28:31], v[158:161], v[240:243], v[28:31]
	v_mfma_f32_16x16x32_bf16 v[24:27], v[166:169], v[240:243], v[24:27]
	v_mfma_f32_16x16x32_bf16 v[12:15], v[158:161], v[248:251], v[12:15]
	v_mfma_f32_16x16x32_bf16 v[8:11], v[166:169], v[248:251], v[8:11]
	s_setprio 0
	s_setprio 1
	v_mfma_f32_16x16x32_bf16 v[52:55], v[170:173], v[220:223], v[52:55]
	v_mfma_f32_16x16x32_bf16 v[48:51], v[178:181], v[220:223], v[48:51]
	v_mfma_f32_16x16x32_bf16 v[36:39], v[170:173], v[228:231], v[36:39]
	v_mfma_f32_16x16x32_bf16 v[32:35], v[178:181], v[228:231], v[32:35]
	v_mfma_f32_16x16x32_bf16 v[20:23], v[170:173], v[236:239], v[20:23]
	v_mfma_f32_16x16x32_bf16 v[16:19], v[178:181], v[236:239], v[16:19]
	v_mfma_f32_16x16x32_bf16 v[4:7], v[170:173], v[244:247], v[4:7]
	v_mfma_f32_16x16x32_bf16 v[0:3], v[178:181], v[244:247], v[0:3]
	v_mfma_f32_16x16x32_bf16 v[52:55], v[174:177], v[224:227], v[52:55]
	v_mfma_f32_16x16x32_bf16 v[48:51], v[182:185], v[224:227], v[48:51]
	v_mfma_f32_16x16x32_bf16 v[36:39], v[174:177], v[232:235], v[36:39]
	v_mfma_f32_16x16x32_bf16 v[32:35], v[182:185], v[232:235], v[32:35]
	v_mfma_f32_16x16x32_bf16 v[20:23], v[174:177], v[240:243], v[20:23]
	v_mfma_f32_16x16x32_bf16 v[16:19], v[182:185], v[240:243], v[16:19]
	v_mfma_f32_16x16x32_bf16 v[4:7], v[174:177], v[248:251], v[4:7]
	v_mfma_f32_16x16x32_bf16 v[0:3], v[182:185], v[248:251], v[0:3]
	s_setprio 0
	s_waitcnt vmcnt(0)
	s_barrier
	s_add_i32 s58, s58, 2
	s_add_u32 s34, s34, 0x100
	s_addc_u32 s35, s35, 0
	s_add_u32 s56, s56, 0x100
	s_addc_u32 s57, s57, 0
	s_cmp_gt_u32 s58, 29
	s_cbranch_scc0 .LBB0_761
